# K-loop dynamic priority inverted: s_setprio 2 during the LDS-read/DMA segment, 0 during the MFMA segment (on top of split LDS waits)
# speedup vs baseline: 1.0055x; 1.0055x over previous
; #define PG8_STAGE(bufoff, gbase, voff) do { _Pragma("unroll") for (int _i = 0; _i < 2; ++_i) \
;         __builtin_amdgcn_global_load_lds((const unsigned*)((const char*)(gbase) + (voff)[_i]), (LAS unsigned*)(lds + (bufoff) + ldsw + _i * 8192), 16, 0, 0); } while (0)
; #define PG8_LDA(dst, b, h) do { _Pragma("unroll") for (int m = 0; m < 4; ++m) _Pragma("unroll") for (int k = 0; k < 2; ++k) dst[m][k] = *(const LAS bf16x8*)(lds + PG8_SA(b, h) + aoff + m * 2048 + k * 1024); } while (0)
; #define PG8_LDB(dst, b, h) do { _Pragma("unroll") for (int n = 0; n < 2; ++n) _Pragma("unroll") for (int k = 0; k < 2; ++k) dst[n][k] = *(const LAS bf16x8*)(lds + PG8_SB(b, h) + boff + n * 2048 + k * 1024); } while (0)
; #define PG8_MMA(ai, bj, At, Bt) do { __builtin_amdgcn_s_setprio(1); _Pragma("unroll") for (int m = 0; m < 4; ++m) _Pragma("unroll") for (int n = 0; n < 2; ++n) _Pragma("unroll") for (int k = 0; k < 2; ++k) \
;         acc[ai][bj][m][n] = __builtin_amdgcn_mfma_f32_16x16x32_bf16(Bt[n][k], At[m][k], acc[ai][bj][m][n], 0, 0, 0); __builtin_amdgcn_s_setprio(0); } while (0)
; #define PG8_WAIT_V(n) asm volatile("s_waitcnt vmcnt(" #n ")" ::: "memory")
; #define PG8_WAIT_L(n) asm volatile("s_waitcnt lgkmcnt(" #n ")" ::: "memory")
; #define PG8_BAR __builtin_amdgcn_s_barrier()
; template <class Epi>
; __device__ __forceinline__ void gemm_phase(LAS unsigned char* lds, const Gemm g, const StaticOrder& S, const Epi& E) {
;     ...
;         for (; t < tend; t += 2) {
;             const bool last = (t == nt - 2);
;             const char* a1 = cA + (size_t)(t + 1) * kstep;
;             const char* a2 = last ? nA : cA + (size_t)(t + 2) * kstep; const char* b2 = last ? nB : cB + (size_t)(t + 2) * kstep;
;             const char* a3 = a2 + kstep; const char* b3 = b2 + kstep;
;             PG8_LDB(B0, 0, 0); PG8_SCHED; PG8_LDA(At, 0, 0); PG8_STAGE(PG8_SA(1, 1), a1 + hstep, voffA);
;             PG8_WAIT_L(8); PG8_BAR; PG8_WAIT_L(0); PG8_MMA(0, 0, At, B0); PG8_BAR; PG8_SCHED;
;             PG8_LDB(B1, 0, 1); PG8_STAGE(PG8_SB(0, 0), b2, voffB);
;             PG8_BAR; PG8_WAIT_L(0); PG8_MMA(0, 1, At, B1); PG8_BAR;
;             PG8_LDA(At, 0, 1); PG8_STAGE(PG8_SA(0, 0), a2, voffA);
;             PG8_BAR; PG8_WAIT_L(0); PG8_MMA(1, 0, At, B0); PG8_BAR; PG8_SCHED;
;             PG8_STAGE(PG8_SB(0, 1), b2 + hstep, voffB);
;             PG8_WAIT_V(6); PG8_BAR; PG8_MMA(1, 1, At, B1); PG8_BAR;
.LBB0_206:
	s_setprio 2
	s_add_i32 s78, 0, 0x10000
	ds_read_b128 v[132:135], v234
	ds_read_b128 v[140:143], v234 offset:2048
	ds_read_b128 v[148:151], v200
	ds_read_b128 v[156:159], v200 offset:2048
	s_add_i32 s76, s2, 1
	s_mov_b32 s47, s2
	s_add_i32 s2, s2, 2
	s_ashr_i32 s77, s76, 31
	s_cmp_eq_u32 s67, s47
	s_cselect_b32 s75, s43, s46
	s_cselect_b32 s74, s42, vcc_hi
	s_cselect_b32 s93, s63, vcc_lo
	s_cselect_b32 s92, s62, s3
	s_lshl_b64 s[76:77], s[76:77], 7
	s_add_u32 s76, s5, s76
	s_addc_u32 s77, s31, s77
	s_add_i32 m0, s11, 0xc000
	ds_read_b128 v[164:167], v200 offset:4096
	ds_read_b128 v[190:193], v200 offset:6144
	ds_read_b128 v[136:139], v234 offset:1024
	ds_read_b128 v[144:147], v234 offset:3072
	ds_read_b128 v[152:155], v200 offset:1024
	ds_read_b128 v[160:163], v200 offset:3072
	ds_read_b128 v[186:189], v200 offset:5120
	ds_read_b128 v[202:205], v200 offset:7168
	global_load_lds_dwordx4 v168, s[76:77]
	s_add_i32 m0, s11, 0xe000
	s_nop 0
	global_load_lds_dwordx4 v172, s[76:77]
	s_waitcnt lgkmcnt(6)
	s_setprio 0
	s_barrier
	v_mfma_f32_16x16x32_bf16 v[128:131], v[132:135], v[148:151], v[128:131]
	v_mfma_f32_16x16x32_bf16 v[124:127], v[140:143], v[148:151], v[124:127]
	v_mfma_f32_16x16x32_bf16 v[112:115], v[132:135], v[156:159], v[112:115]
	v_mfma_f32_16x16x32_bf16 v[108:111], v[140:143], v[156:159], v[108:111]
	v_mfma_f32_16x16x32_bf16 v[96:99], v[132:135], v[164:167], v[96:99]
	v_mfma_f32_16x16x32_bf16 v[92:95], v[140:143], v[164:167], v[92:95]
	v_mfma_f32_16x16x32_bf16 v[80:83], v[132:135], v[190:193], v[80:83]
	v_mfma_f32_16x16x32_bf16 v[76:79], v[140:143], v[190:193], v[76:79]
	s_waitcnt lgkmcnt(0)
	v_mfma_f32_16x16x32_bf16 v[128:131], v[136:139], v[152:155], v[128:131]
	v_mfma_f32_16x16x32_bf16 v[124:127], v[144:147], v[152:155], v[124:127]
	v_mfma_f32_16x16x32_bf16 v[112:115], v[136:139], v[160:163], v[112:115]
	v_mfma_f32_16x16x32_bf16 v[108:111], v[144:147], v[160:163], v[108:111]
	v_mfma_f32_16x16x32_bf16 v[96:99], v[136:139], v[186:189], v[96:99]
	v_mfma_f32_16x16x32_bf16 v[92:95], v[144:147], v[186:189], v[92:95]
	v_mfma_f32_16x16x32_bf16 v[80:83], v[136:139], v[202:205], v[80:83]
	v_mfma_f32_16x16x32_bf16 v[76:79], v[144:147], v[202:205], v[76:79]
	s_barrier
	s_setprio 2
	s_add_i32 s47, 0, 0x14000
	s_add_i32 s76, s78, s6
	s_mov_b32 m0, s76
	ds_read_b128 v[206:209], v235
	ds_read_b128 v[226:229], v235 offset:2048
	ds_read_b128 v[222:225], v235 offset:1024
	ds_read_b128 v[230:233], v235 offset:3072
	global_load_lds_dwordx4 v170, s[92:93]
	s_add_i32 m0, s76, 0x2000
	s_nop 0
	global_load_lds_dwordx4 v174, s[92:93]
	s_waitcnt lgkmcnt(2)
	s_setprio 0
	s_barrier
	v_mfma_f32_16x16x32_bf16 v[120:123], v[206:209], v[148:151], v[120:123]
	v_mfma_f32_16x16x32_bf16 v[116:119], v[226:229], v[148:151], v[116:119]
	v_mfma_f32_16x16x32_bf16 v[104:107], v[206:209], v[156:159], v[104:107]
	v_mfma_f32_16x16x32_bf16 v[100:103], v[226:229], v[156:159], v[100:103]
	v_mfma_f32_16x16x32_bf16 v[88:91], v[206:209], v[164:167], v[88:91]
	v_mfma_f32_16x16x32_bf16 v[84:87], v[226:229], v[164:167], v[84:87]
	v_mfma_f32_16x16x32_bf16 v[72:75], v[206:209], v[190:193], v[72:75]
	v_mfma_f32_16x16x32_bf16 v[68:71], v[226:229], v[190:193], v[68:71]
	s_waitcnt lgkmcnt(0)
	v_mfma_f32_16x16x32_bf16 v[120:123], v[222:225], v[152:155], v[120:123]
	v_mfma_f32_16x16x32_bf16 v[116:119], v[230:233], v[152:155], v[116:119]
	v_mfma_f32_16x16x32_bf16 v[104:107], v[222:225], v[160:163], v[104:107]
	v_mfma_f32_16x16x32_bf16 v[100:103], v[230:233], v[160:163], v[100:103]
	v_mfma_f32_16x16x32_bf16 v[88:91], v[222:225], v[186:189], v[88:91]
	v_mfma_f32_16x16x32_bf16 v[84:87], v[230:233], v[186:189], v[84:87]
	v_mfma_f32_16x16x32_bf16 v[72:75], v[222:225], v[202:205], v[72:75]
	v_mfma_f32_16x16x32_bf16 v[68:71], v[230:233], v[202:205], v[68:71]
	s_mov_b32 m0, s11
	s_barrier
	s_setprio 2
	ds_read_b128 v[148:151], v200 offset:16384
	ds_read_b128 v[156:159], v200 offset:18432
	ds_read_b128 v[164:167], v200 offset:20480
	ds_read_b128 v[190:193], v200 offset:22528
	ds_read_b128 v[152:155], v200 offset:17408
	ds_read_b128 v[160:163], v200 offset:19456
	ds_read_b128 v[186:189], v200 offset:21504
	ds_read_b128 v[202:205], v200 offset:23552
	global_load_lds_dwordx4 v168, s[74:75]
	s_mov_b32 m0, s70
	s_nop 0
	global_load_lds_dwordx4 v172, s[74:75]
	s_waitcnt lgkmcnt(4)
	s_setprio 0
	s_barrier
	v_mfma_f32_16x16x32_bf16 v[64:67], v[132:135], v[148:151], v[64:67]
	v_mfma_f32_16x16x32_bf16 v[60:63], v[140:143], v[148:151], v[60:63]
	v_mfma_f32_16x16x32_bf16 v[48:51], v[132:135], v[156:159], v[48:51]
	v_mfma_f32_16x16x32_bf16 v[44:47], v[140:143], v[156:159], v[44:47]
	v_mfma_f32_16x16x32_bf16 v[32:35], v[132:135], v[164:167], v[32:35]
	v_mfma_f32_16x16x32_bf16 v[28:31], v[140:143], v[164:167], v[28:31]
	v_mfma_f32_16x16x32_bf16 v[16:19], v[132:135], v[190:193], v[16:19]
	v_mfma_f32_16x16x32_bf16 v[12:15], v[140:143], v[190:193], v[12:15]
	s_waitcnt lgkmcnt(0)
	v_mfma_f32_16x16x32_bf16 v[64:67], v[136:139], v[152:155], v[64:67]
	v_mfma_f32_16x16x32_bf16 v[60:63], v[144:147], v[152:155], v[60:63]
	v_mfma_f32_16x16x32_bf16 v[48:51], v[136:139], v[160:163], v[48:51]
	v_mfma_f32_16x16x32_bf16 v[44:47], v[144:147], v[160:163], v[44:47]
	v_mfma_f32_16x16x32_bf16 v[32:35], v[136:139], v[186:189], v[32:35]
	v_mfma_f32_16x16x32_bf16 v[28:31], v[144:147], v[186:189], v[28:31]
	v_mfma_f32_16x16x32_bf16 v[16:19], v[136:139], v[202:205], v[16:19]
	v_mfma_f32_16x16x32_bf16 v[12:15], v[144:147], v[202:205], v[12:15]
	s_barrier
	s_setprio 2
	s_add_u32 s76, s92, s13
	s_addc_u32 s77, s93, 0
	s_add_i32 s47, s47, s6
	s_mov_b32 m0, s47
	s_nop 0
	global_load_lds_dwordx4 v170, s[76:77]
	s_add_i32 m0, s47, 0x2000
	s_nop 0
	global_load_lds_dwordx4 v174, s[76:77]
	s_waitcnt vmcnt(6)
	s_setprio 0
	s_barrier
; #define PG8_STAGE(bufoff, gbase, voff) do { _Pragma("unroll") for (int _i = 0; _i < 2; ++_i) \
;         __builtin_amdgcn_global_load_lds((const unsigned*)((const char*)(gbase) + (voff)[_i]), (LAS unsigned*)(lds + (bufoff) + ldsw + _i * 8192), 16, 0, 0); } while (0)
; #define PG8_LDA(dst, b, h) do { _Pragma("unroll") for (int m = 0; m < 4; ++m) _Pragma("unroll") for (int k = 0; k < 2; ++k) dst[m][k] = *(const LAS bf16x8*)(lds + PG8_SA(b, h) + aoff + m * 2048 + k * 1024); } while (0)
; #define PG8_LDB(dst, b, h) do { _Pragma("unroll") for (int n = 0; n < 2; ++n) _Pragma("unroll") for (int k = 0; k < 2; ++k) dst[n][k] = *(const LAS bf16x8*)(lds + PG8_SB(b, h) + boff + n * 2048 + k * 1024); } while (0)
; #define PG8_MMA(ai, bj, At, Bt) do { __builtin_amdgcn_s_setprio(1); _Pragma("unroll") for (int m = 0; m < 4; ++m) _Pragma("unroll") for (int n = 0; n < 2; ++n) _Pragma("unroll") for (int k = 0; k < 2; ++k) \
;         acc[ai][bj][m][n] = __builtin_amdgcn_mfma_f32_16x16x32_bf16(Bt[n][k], At[m][k], acc[ai][bj][m][n], 0, 0, 0); __builtin_amdgcn_s_setprio(0); } while (0)
; #define PG8_WAIT_V(n) asm volatile("s_waitcnt vmcnt(" #n ")" ::: "memory")
; #define PG8_WAIT_L(n) asm volatile("s_waitcnt lgkmcnt(" #n ")" ::: "memory")
; #define PG8_BAR __builtin_amdgcn_s_barrier()
; #define PG8_SCHED __builtin_amdgcn_sched_barrier(0)
; template <class Epi>
; __device__ __forceinline__ void gemm_phase(LAS unsigned char* lds, const Gemm g, const StaticOrder& S, const Epi& E) {
;     ...
;             PG8_WAIT_V(6); PG8_BAR; PG8_MMA(1, 1, At, B1); PG8_BAR;
;             PG8_LDB(B0, 1, 0); PG8_SCHED; PG8_LDA(At, 1, 0); PG8_STAGE(PG8_SA(0, 1), a2 + hstep, voffA);
;             PG8_WAIT_L(8); PG8_BAR; PG8_WAIT_L(0); PG8_MMA(0, 0, At, B0); PG8_BAR; PG8_SCHED;
;             PG8_LDB(B1, 1, 1); PG8_STAGE(PG8_SB(1, 0), b3, voffB);
;             PG8_BAR; PG8_WAIT_L(0); PG8_MMA(0, 1, At, B1); PG8_BAR;
	v_mfma_f32_16x16x32_bf16 v[56:59], v[206:209], v[148:151], v[56:59]
	v_mfma_f32_16x16x32_bf16 v[52:55], v[226:229], v[148:151], v[52:55]
	v_mfma_f32_16x16x32_bf16 v[40:43], v[206:209], v[156:159], v[40:43]
	v_mfma_f32_16x16x32_bf16 v[36:39], v[226:229], v[156:159], v[36:39]
	v_mfma_f32_16x16x32_bf16 v[24:27], v[206:209], v[164:167], v[24:27]
	v_mfma_f32_16x16x32_bf16 v[20:23], v[226:229], v[164:167], v[20:23]
	v_mfma_f32_16x16x32_bf16 v[8:11], v[206:209], v[190:193], v[8:11]
	v_mfma_f32_16x16x32_bf16 v[4:7], v[226:229], v[190:193], v[4:7]
	v_mfma_f32_16x16x32_bf16 v[56:59], v[222:225], v[152:155], v[56:59]
	v_mfma_f32_16x16x32_bf16 v[52:55], v[230:233], v[152:155], v[52:55]
	v_mfma_f32_16x16x32_bf16 v[40:43], v[222:225], v[160:163], v[40:43]
	v_mfma_f32_16x16x32_bf16 v[36:39], v[230:233], v[160:163], v[36:39]
	v_mfma_f32_16x16x32_bf16 v[24:27], v[222:225], v[186:189], v[24:27]
	v_mfma_f32_16x16x32_bf16 v[20:23], v[230:233], v[186:189], v[20:23]
	v_mfma_f32_16x16x32_bf16 v[8:11], v[222:225], v[202:205], v[8:11]
	v_mfma_f32_16x16x32_bf16 v[4:7], v[230:233], v[202:205], v[4:7]
	s_add_i32 s47, 0, 0x18000
	s_barrier
	s_setprio 2
	ds_read_b128 v[132:135], v236
	ds_read_b128 v[140:143], v236 offset:2048
	ds_read_b128 v[148:151], v200 offset:32768
	ds_read_b128 v[156:159], v200 offset:34816
	s_add_u32 s76, s74, s13
	s_addc_u32 s77, s75, 0
	s_mov_b32 m0, s71
	ds_read_b128 v[164:167], v200 offset:36864
	ds_read_b128 v[190:193], v200 offset:38912
	ds_read_b128 v[136:139], v236 offset:1024
	ds_read_b128 v[144:147], v236 offset:3072
	ds_read_b128 v[152:155], v200 offset:33792
	ds_read_b128 v[160:163], v200 offset:35840
	ds_read_b128 v[186:189], v200 offset:37888
	ds_read_b128 v[202:205], v200 offset:39936
	global_load_lds_dwordx4 v168, s[76:77]
	s_mov_b32 m0, s19
	s_nop 0
	global_load_lds_dwordx4 v172, s[76:77]
	s_waitcnt lgkmcnt(6)
	s_setprio 0
	s_barrier
	v_mfma_f32_16x16x32_bf16 v[128:131], v[132:135], v[148:151], v[128:131]
	v_mfma_f32_16x16x32_bf16 v[124:127], v[140:143], v[148:151], v[124:127]
	v_mfma_f32_16x16x32_bf16 v[112:115], v[132:135], v[156:159], v[112:115]
	v_mfma_f32_16x16x32_bf16 v[108:111], v[140:143], v[156:159], v[108:111]
	v_mfma_f32_16x16x32_bf16 v[96:99], v[132:135], v[164:167], v[96:99]
	v_mfma_f32_16x16x32_bf16 v[92:95], v[140:143], v[164:167], v[92:95]
	v_mfma_f32_16x16x32_bf16 v[80:83], v[132:135], v[190:193], v[80:83]
	v_mfma_f32_16x16x32_bf16 v[76:79], v[140:143], v[190:193], v[76:79]
	s_waitcnt lgkmcnt(0)
	v_mfma_f32_16x16x32_bf16 v[128:131], v[136:139], v[152:155], v[128:131]
	v_mfma_f32_16x16x32_bf16 v[124:127], v[144:147], v[152:155], v[124:127]
	v_mfma_f32_16x16x32_bf16 v[112:115], v[136:139], v[160:163], v[112:115]
	v_mfma_f32_16x16x32_bf16 v[108:111], v[144:147], v[160:163], v[108:111]
	v_mfma_f32_16x16x32_bf16 v[96:99], v[136:139], v[186:189], v[96:99]
	v_mfma_f32_16x16x32_bf16 v[92:95], v[144:147], v[186:189], v[92:95]
	v_mfma_f32_16x16x32_bf16 v[80:83], v[136:139], v[202:205], v[80:83]
	v_mfma_f32_16x16x32_bf16 v[76:79], v[144:147], v[202:205], v[76:79]
	s_barrier
	s_setprio 2
	s_add_i32 s47, s47, s6
	s_add_u32 s76, s92, 0x80
	s_addc_u32 s77, s93, 0
	s_mov_b32 m0, s47
	ds_read_b128 v[206:209], v237
	ds_read_b128 v[226:229], v237 offset:2048
	ds_read_b128 v[222:225], v237 offset:1024
	ds_read_b128 v[230:233], v237 offset:3072
	global_load_lds_dwordx4 v170, s[76:77]
	s_add_i32 m0, s47, 0x2000
	s_nop 0
	global_load_lds_dwordx4 v174, s[76:77]
	s_waitcnt lgkmcnt(2)
	s_setprio 0
	s_barrier
; #define PG8_STAGE(bufoff, gbase, voff) do { _Pragma("unroll") for (int _i = 0; _i < 2; ++_i) \
;         __builtin_amdgcn_global_load_lds((const unsigned*)((const char*)(gbase) + (voff)[_i]), (LAS unsigned*)(lds + (bufoff) + ldsw + _i * 8192), 16, 0, 0); } while (0)
; #define PG8_LDA(dst, b, h) do { _Pragma("unroll") for (int m = 0; m < 4; ++m) _Pragma("unroll") for (int k = 0; k < 2; ++k) dst[m][k] = *(const LAS bf16x8*)(lds + PG8_SA(b, h) + aoff + m * 2048 + k * 1024); } while (0)
; #define PG8_MMA(ai, bj, At, Bt) do { __builtin_amdgcn_s_setprio(1); _Pragma("unroll") for (int m = 0; m < 4; ++m) _Pragma("unroll") for (int n = 0; n < 2; ++n) _Pragma("unroll") for (int k = 0; k < 2; ++k) \
;         acc[ai][bj][m][n] = __builtin_amdgcn_mfma_f32_16x16x32_bf16(Bt[n][k], At[m][k], acc[ai][bj][m][n], 0, 0, 0); __builtin_amdgcn_s_setprio(0); } while (0)
; #define PG8_WAIT_V(n) asm volatile("s_waitcnt vmcnt(" #n ")" ::: "memory")
; #define PG8_WAIT_L(n) asm volatile("s_waitcnt lgkmcnt(" #n ")" ::: "memory")
; #define PG8_BAR __builtin_amdgcn_s_barrier()
; #define PG8_SCHED __builtin_amdgcn_sched_barrier(0)
; template <class Epi>
; __device__ __forceinline__ void gemm_phase(LAS unsigned char* lds, const Gemm g, const StaticOrder& S, const Epi& E) {
;     ...
;             PG8_BAR; PG8_WAIT_L(0); PG8_MMA(0, 1, At, B1); PG8_BAR;
;             PG8_LDA(At, 1, 1); PG8_STAGE(PG8_SA(1, 0), a3, voffA);
;             PG8_BAR; PG8_WAIT_L(0); PG8_MMA(1, 0, At, B0); PG8_BAR; PG8_SCHED;
;             PG8_STAGE(PG8_SB(1, 1), b3 + hstep, voffB);
;             PG8_WAIT_V(6); PG8_BAR; PG8_MMA(1, 1, At, B1); PG8_BAR;
	v_mfma_f32_16x16x32_bf16 v[120:123], v[206:209], v[148:151], v[120:123]
	v_mfma_f32_16x16x32_bf16 v[116:119], v[226:229], v[148:151], v[116:119]
	v_mfma_f32_16x16x32_bf16 v[104:107], v[206:209], v[156:159], v[104:107]
	v_mfma_f32_16x16x32_bf16 v[100:103], v[226:229], v[156:159], v[100:103]
	v_mfma_f32_16x16x32_bf16 v[88:91], v[206:209], v[164:167], v[88:91]
	v_mfma_f32_16x16x32_bf16 v[84:87], v[226:229], v[164:167], v[84:87]
	v_mfma_f32_16x16x32_bf16 v[72:75], v[206:209], v[190:193], v[72:75]
	v_mfma_f32_16x16x32_bf16 v[68:71], v[226:229], v[190:193], v[68:71]
	s_waitcnt lgkmcnt(0)
	v_mfma_f32_16x16x32_bf16 v[120:123], v[222:225], v[152:155], v[120:123]
	v_mfma_f32_16x16x32_bf16 v[116:119], v[230:233], v[152:155], v[116:119]
	v_mfma_f32_16x16x32_bf16 v[104:107], v[222:225], v[160:163], v[104:107]
	v_mfma_f32_16x16x32_bf16 v[100:103], v[230:233], v[160:163], v[100:103]
	v_mfma_f32_16x16x32_bf16 v[88:91], v[222:225], v[186:189], v[88:91]
	v_mfma_f32_16x16x32_bf16 v[84:87], v[230:233], v[186:189], v[84:87]
	v_mfma_f32_16x16x32_bf16 v[72:75], v[222:225], v[202:205], v[72:75]
	v_mfma_f32_16x16x32_bf16 v[68:71], v[230:233], v[202:205], v[68:71]
	s_mov_b32 m0, s33
	s_add_u32 s76, s74, 0x80
	s_addc_u32 s77, s75, 0
	s_barrier
	s_setprio 2
	ds_read_b128 v[148:151], v200 offset:49152
	ds_read_b128 v[156:159], v200 offset:51200
	ds_read_b128 v[164:167], v200 offset:53248
	ds_read_b128 v[190:193], v200 offset:55296
	ds_read_b128 v[152:155], v200 offset:50176
	ds_read_b128 v[160:163], v200 offset:52224
	ds_read_b128 v[186:189], v200 offset:54272
	ds_read_b128 v[202:205], v200 offset:56320
	global_load_lds_dwordx4 v168, s[76:77]
	s_mov_b32 m0, s66
	s_nop 0
	global_load_lds_dwordx4 v172, s[76:77]
	s_waitcnt lgkmcnt(4)
	s_setprio 0
	s_barrier
	v_mfma_f32_16x16x32_bf16 v[64:67], v[132:135], v[148:151], v[64:67]
	v_mfma_f32_16x16x32_bf16 v[60:63], v[140:143], v[148:151], v[60:63]
	v_mfma_f32_16x16x32_bf16 v[48:51], v[132:135], v[156:159], v[48:51]
	v_mfma_f32_16x16x32_bf16 v[44:47], v[140:143], v[156:159], v[44:47]
	v_mfma_f32_16x16x32_bf16 v[32:35], v[132:135], v[164:167], v[32:35]
	v_mfma_f32_16x16x32_bf16 v[28:31], v[140:143], v[164:167], v[28:31]
	v_mfma_f32_16x16x32_bf16 v[16:19], v[132:135], v[190:193], v[16:19]
	v_mfma_f32_16x16x32_bf16 v[12:15], v[140:143], v[190:193], v[12:15]
	s_waitcnt lgkmcnt(0)
	v_mfma_f32_16x16x32_bf16 v[64:67], v[136:139], v[152:155], v[64:67]
	v_mfma_f32_16x16x32_bf16 v[60:63], v[144:147], v[152:155], v[60:63]
	v_mfma_f32_16x16x32_bf16 v[48:51], v[136:139], v[160:163], v[48:51]
	v_mfma_f32_16x16x32_bf16 v[44:47], v[144:147], v[160:163], v[44:47]
	v_mfma_f32_16x16x32_bf16 v[32:35], v[136:139], v[186:189], v[32:35]
	v_mfma_f32_16x16x32_bf16 v[28:31], v[144:147], v[186:189], v[28:31]
	v_mfma_f32_16x16x32_bf16 v[16:19], v[136:139], v[202:205], v[16:19]
	v_mfma_f32_16x16x32_bf16 v[12:15], v[144:147], v[202:205], v[12:15]
	s_barrier
	s_setprio 2
	s_add_i32 s47, s6, 0x1c000
	s_add_u32 s76, s92, s13
	s_addc_u32 s77, s93, 0
	s_add_u32 s76, s76, 0x80
	s_addc_u32 s77, s77, 0
	s_mov_b32 m0, s47
	s_nop 0
	global_load_lds_dwordx4 v170, s[76:77]
	s_add_i32 m0, s47, 0x2000
	s_nop 0
	global_load_lds_dwordx4 v174, s[76:77]
	s_waitcnt vmcnt(6)
	s_setprio 0
	s_barrier
	v_mfma_f32_16x16x32_bf16 v[56:59], v[206:209], v[148:151], v[56:59]
	v_mfma_f32_16x16x32_bf16 v[52:55], v[226:229], v[148:151], v[52:55]
	v_mfma_f32_16x16x32_bf16 v[40:43], v[206:209], v[156:159], v[40:43]
	v_mfma_f32_16x16x32_bf16 v[36:39], v[226:229], v[156:159], v[36:39]
	v_mfma_f32_16x16x32_bf16 v[24:27], v[206:209], v[164:167], v[24:27]
	v_mfma_f32_16x16x32_bf16 v[20:23], v[226:229], v[164:167], v[20:23]
	v_mfma_f32_16x16x32_bf16 v[8:11], v[206:209], v[190:193], v[8:11]
	v_mfma_f32_16x16x32_bf16 v[4:7], v[226:229], v[190:193], v[4:7]
	v_mfma_f32_16x16x32_bf16 v[56:59], v[222:225], v[152:155], v[56:59]
	v_mfma_f32_16x16x32_bf16 v[52:55], v[230:233], v[152:155], v[52:55]
	v_mfma_f32_16x16x32_bf16 v[40:43], v[222:225], v[160:163], v[40:43]
	v_mfma_f32_16x16x32_bf16 v[36:39], v[230:233], v[160:163], v[36:39]
	v_mfma_f32_16x16x32_bf16 v[24:27], v[222:225], v[186:189], v[24:27]
	v_mfma_f32_16x16x32_bf16 v[20:23], v[230:233], v[186:189], v[20:23]
	v_mfma_f32_16x16x32_bf16 v[8:11], v[222:225], v[202:205], v[8:11]
	v_mfma_f32_16x16x32_bf16 v[4:7], v[230:233], v[202:205], v[4:7]
	s_add_u32 s3, s3, 0x100
	s_addc_u32 vcc_lo, vcc_lo, 0
	s_add_u32 vcc_hi, vcc_hi, 0x100
	s_addc_u32 s46, s46, 0
	s_cmp_lt_i32 s2, s57
	s_barrier
	s_cbranch_scc1 .LBB0_206
	s_movk_i32 s92, 0x90
	s_mov_b32 s93, 0x3f317217
